# speedup vs baseline: 1.0075x; 1.0037x over previous
; __device__ __forceinline__ void attn_block(const Params& p, int bt_raw, char* smem) {
;     ...
;     unsigned bits = 0;
; #pragma unroll
;     for (int i = 0; i < 4; ++i) {
;       int J = (lane & 7) * 4 + i;
;       int rank = 0;
; #pragma unroll 1
;       for (int J2 = 0; J2 < 32; ++J2) {
;         float o = imp[tk * 32 + J2];
;         rank += (o > vals[i] || (o == vals[i] && J2 < J)) ? 1 : 0;
;       }
;       if (rank < 8) bits |= (1u << J);
;     }
.LBB0_334:
	s_or_b64 exec, exec, s[4:5]
	s_mov_b64 s[4:5], 0x2c00
	v_lshl_add_u32 v59, v52, 2, v55
	s_waitcnt lgkmcnt(0)
	v_mov_b32_e32 v49, v60
	v_mov_b32_e32 v51, v54
	v_lshlrev_b32_e32 v171, 7, v149
	v_ashrrev_i32_e32 v151, 31, v150
	v_ashrrev_i32_e32 v149, 31, v148
	s_lshl_b32 s51, s20, 7
	v_lshl_add_u64 v[164:165], v[62:63], 0, s[4:5]
	s_lshl_b64 s[2:3], s[2:3], 18
	s_barrier
	ds_write_b128 v59, v[48:51]
	v_mov_b32_e32 v49, v48
	v_mov_b32_e32 v51, v52
	v_add3_u32 v57, v187, v57, s39
	s_mov_b32 s15, 1
	s_mov_b32 s20, 0
	v_mov_b32_e32 v59, 0
	v_mov_b32_e32 v61, 0
	s_mov_b32 s28, 0
	s_waitcnt lgkmcnt(0)
	s_barrier
	ds_read_b64 v[112:113], v57
	ds_read_b64 v[114:115], v57 offset:8
	ds_read_b64 v[116:117], v57 offset:16
	ds_read_b64 v[118:119], v57 offset:24
	ds_read_b64 v[120:121], v57 offset:32
	ds_read_b64 v[122:123], v57 offset:40
	ds_read_b64 v[124:125], v57 offset:48
	ds_read_b64 v[126:127], v57 offset:56
	ds_read_b64 v[220:221], v57 offset:64
	ds_read_b64 v[222:223], v57 offset:72
	ds_read_b64 v[224:225], v57 offset:80
	ds_read_b64 v[226:227], v57 offset:88
	ds_read_b64 v[228:229], v57 offset:96
	ds_read_b64 v[230:231], v57 offset:104
	ds_read_b64 v[232:233], v57 offset:112
	ds_read_b64 v[234:235], v57 offset:120
	v_mov_b32_e32 v128, 0
	v_mov_b32_e32 v129, 0
	v_mov_b32_e32 v130, 0
	v_mov_b32_e32 v131, 0
	s_waitcnt lgkmcnt(14)
	v_cmp_gt_u32_e64 s[8:9], v52, 0
	v_cmp_gt_f32_e64 s[4:5], v112, v48
	v_cmp_eq_f32_e64 s[6:7], v112, v48
	v_cmp_ge_f32_e64 vcc, v112, v60
	s_and_b64 s[6:7], s[6:7], s[8:9]
	s_or_b64 s[4:5], s[4:5], s[6:7]
	v_addc_co_u32_e64 v128, s[4:5], 0, v128, s[4:5]
	v_addc_co_u32_e32 v129, vcc, 0, v129, vcc
	v_cmp_ge_f32_e64 s[4:5], v112, v50
	v_cmp_ge_f32_e64 vcc, v112, v54
	s_nop 1
	v_addc_co_u32_e64 v130, s[4:5], 0, v130, s[4:5]
	v_addc_co_u32_e32 v131, vcc, 0, v131, vcc
	v_cmp_gt_f32_e64 s[4:5], v113, v48
	v_cmp_eq_f32_e64 s[6:7], v113, v48
	v_cmp_gt_f32_e64 vcc, v113, v60
	v_cmp_eq_f32_e64 s[12:13], v113, v60
	s_and_b64 s[6:7], s[6:7], s[8:9]
	s_and_b64 s[12:13], s[12:13], s[8:9]
	s_or_b64 s[4:5], s[4:5], s[6:7]
	s_or_b64 vcc, vcc, s[12:13]
	v_addc_co_u32_e64 v128, s[4:5], 0, v128, s[4:5]
	v_addc_co_u32_e32 v129, vcc, 0, v129, vcc
	v_cmp_ge_f32_e64 s[4:5], v113, v50
	v_cmp_ge_f32_e64 vcc, v113, v54
	s_nop 1
	v_addc_co_u32_e64 v130, s[4:5], 0, v130, s[4:5]
	v_addc_co_u32_e32 v131, vcc, 0, v131, vcc
	v_cmp_gt_f32_e64 s[4:5], v114, v48
	v_cmp_eq_f32_e64 s[6:7], v114, v48
	v_cmp_gt_f32_e64 vcc, v114, v60
	v_cmp_eq_f32_e64 s[12:13], v114, v60
	s_and_b64 s[6:7], s[6:7], s[8:9]
	s_and_b64 s[12:13], s[12:13], s[8:9]
	s_or_b64 s[4:5], s[4:5], s[6:7]
	s_or_b64 vcc, vcc, s[12:13]
	v_addc_co_u32_e64 v128, s[4:5], 0, v128, s[4:5]
	v_addc_co_u32_e32 v129, vcc, 0, v129, vcc
	v_cmp_gt_f32_e64 s[4:5], v114, v50
	v_cmp_eq_f32_e64 s[6:7], v114, v50
	v_cmp_ge_f32_e64 vcc, v114, v54
	s_and_b64 s[6:7], s[6:7], s[8:9]
	s_or_b64 s[4:5], s[4:5], s[6:7]
	v_addc_co_u32_e64 v130, s[4:5], 0, v130, s[4:5]
	v_addc_co_u32_e32 v131, vcc, 0, v131, vcc
	v_cmp_gt_f32_e64 s[4:5], v115, v48
	v_cmp_eq_f32_e64 s[6:7], v115, v48
	v_cmp_gt_f32_e64 vcc, v115, v60
	v_cmp_eq_f32_e64 s[12:13], v115, v60
	s_and_b64 s[6:7], s[6:7], s[8:9]
	s_and_b64 s[12:13], s[12:13], s[8:9]
	s_or_b64 s[4:5], s[4:5], s[6:7]
	s_or_b64 vcc, vcc, s[12:13]
	v_addc_co_u32_e64 v128, s[4:5], 0, v128, s[4:5]
	v_addc_co_u32_e32 v129, vcc, 0, v129, vcc
	v_cmp_gt_f32_e64 s[4:5], v115, v50
	v_cmp_eq_f32_e64 s[6:7], v115, v50
	v_cmp_gt_f32_e64 vcc, v115, v54
	v_cmp_eq_f32_e64 s[12:13], v115, v54
	s_and_b64 s[6:7], s[6:7], s[8:9]
	s_and_b64 s[12:13], s[12:13], s[8:9]
	s_or_b64 s[4:5], s[4:5], s[6:7]
	s_or_b64 vcc, vcc, s[12:13]
	v_addc_co_u32_e64 v130, s[4:5], 0, v130, s[4:5]
	v_addc_co_u32_e32 v131, vcc, 0, v131, vcc
	s_waitcnt lgkmcnt(12)
	v_cmp_gt_u32_e64 s[10:11], v52, 4
	v_cmp_gt_f32_e64 s[4:5], v116, v48
	v_cmp_eq_f32_e64 s[6:7], v116, v48
	v_cmp_gt_f32_e64 vcc, v116, v60
	v_cmp_eq_f32_e64 s[12:13], v116, v60
	s_and_b64 s[6:7], s[6:7], s[10:11]
	s_and_b64 s[12:13], s[12:13], s[8:9]
	s_or_b64 s[4:5], s[4:5], s[6:7]
	s_or_b64 vcc, vcc, s[12:13]
	v_addc_co_u32_e64 v128, s[4:5], 0, v128, s[4:5]
	v_addc_co_u32_e32 v129, vcc, 0, v129, vcc
	v_cmp_gt_f32_e64 s[4:5], v116, v50
	v_cmp_eq_f32_e64 s[6:7], v116, v50
	v_cmp_gt_f32_e64 vcc, v116, v54
	v_cmp_eq_f32_e64 s[12:13], v116, v54
	s_and_b64 s[6:7], s[6:7], s[8:9]
	s_and_b64 s[12:13], s[12:13], s[8:9]
	s_or_b64 s[4:5], s[4:5], s[6:7]
	s_or_b64 vcc, vcc, s[12:13]
	v_addc_co_u32_e64 v130, s[4:5], 0, v130, s[4:5]
	v_addc_co_u32_e32 v131, vcc, 0, v131, vcc
	v_cmp_gt_f32_e64 s[4:5], v117, v48
	v_cmp_eq_f32_e64 s[6:7], v117, v48
	v_cmp_gt_f32_e64 vcc, v117, v60
	v_cmp_eq_f32_e64 s[12:13], v117, v60
	s_and_b64 s[6:7], s[6:7], s[10:11]
	s_and_b64 s[12:13], s[12:13], s[10:11]
	s_or_b64 s[4:5], s[4:5], s[6:7]
	s_or_b64 vcc, vcc, s[12:13]
	v_addc_co_u32_e64 v128, s[4:5], 0, v128, s[4:5]
	v_addc_co_u32_e32 v129, vcc, 0, v129, vcc
	v_cmp_gt_f32_e64 s[4:5], v117, v50
	v_cmp_eq_f32_e64 s[6:7], v117, v50
	v_cmp_gt_f32_e64 vcc, v117, v54
	v_cmp_eq_f32_e64 s[12:13], v117, v54
	s_and_b64 s[6:7], s[6:7], s[8:9]
	s_and_b64 s[12:13], s[12:13], s[8:9]
	s_or_b64 s[4:5], s[4:5], s[6:7]
	s_or_b64 vcc, vcc, s[12:13]
	v_addc_co_u32_e64 v130, s[4:5], 0, v130, s[4:5]
	v_addc_co_u32_e32 v131, vcc, 0, v131, vcc
	v_cmp_gt_f32_e64 s[4:5], v118, v48
	v_cmp_eq_f32_e64 s[6:7], v118, v48
	v_cmp_gt_f32_e64 vcc, v118, v60
	v_cmp_eq_f32_e64 s[12:13], v118, v60
	s_and_b64 s[6:7], s[6:7], s[10:11]
	s_and_b64 s[12:13], s[12:13], s[10:11]
	s_or_b64 s[4:5], s[4:5], s[6:7]
	s_or_b64 vcc, vcc, s[12:13]
	v_addc_co_u32_e64 v128, s[4:5], 0, v128, s[4:5]
	v_addc_co_u32_e32 v129, vcc, 0, v129, vcc
	v_cmp_gt_f32_e64 s[4:5], v118, v50
	v_cmp_eq_f32_e64 s[6:7], v118, v50
	v_cmp_gt_f32_e64 vcc, v118, v54
	v_cmp_eq_f32_e64 s[12:13], v118, v54
	s_and_b64 s[6:7], s[6:7], s[10:11]
	s_and_b64 s[12:13], s[12:13], s[8:9]
	s_or_b64 s[4:5], s[4:5], s[6:7]
	s_or_b64 vcc, vcc, s[12:13]
	v_addc_co_u32_e64 v130, s[4:5], 0, v130, s[4:5]
	v_addc_co_u32_e32 v131, vcc, 0, v131, vcc
	v_cmp_gt_f32_e64 s[4:5], v119, v48
	v_cmp_eq_f32_e64 s[6:7], v119, v48
	v_cmp_gt_f32_e64 vcc, v119, v60
	v_cmp_eq_f32_e64 s[12:13], v119, v60
	s_and_b64 s[6:7], s[6:7], s[10:11]
	s_and_b64 s[12:13], s[12:13], s[10:11]
	s_or_b64 s[4:5], s[4:5], s[6:7]
	s_or_b64 vcc, vcc, s[12:13]
	v_addc_co_u32_e64 v128, s[4:5], 0, v128, s[4:5]
	v_addc_co_u32_e32 v129, vcc, 0, v129, vcc
	v_cmp_gt_f32_e64 s[4:5], v119, v50
	v_cmp_eq_f32_e64 s[6:7], v119, v50
	v_cmp_gt_f32_e64 vcc, v119, v54
	v_cmp_eq_f32_e64 s[12:13], v119, v54
	s_and_b64 s[6:7], s[6:7], s[10:11]
	s_and_b64 s[12:13], s[12:13], s[10:11]
	s_or_b64 s[4:5], s[4:5], s[6:7]
	s_or_b64 vcc, vcc, s[12:13]
	v_addc_co_u32_e64 v130, s[4:5], 0, v130, s[4:5]
	v_addc_co_u32_e32 v131, vcc, 0, v131, vcc
	s_waitcnt lgkmcnt(10)
; __device__ __forceinline__ void attn_block(const Params& p, int bt_raw, char* smem) {
;     ...
;     unsigned bits = 0;
; #pragma unroll
;     for (int i = 0; i < 4; ++i) {
;       int J = (lane & 7) * 4 + i;
;       int rank = 0;
; #pragma unroll 1
;       for (int J2 = 0; J2 < 32; ++J2) {
;         float o = imp[tk * 32 + J2];
;         rank += (o > vals[i] || (o == vals[i] && J2 < J)) ? 1 : 0;
;       }
;       if (rank < 8) bits |= (1u << J);
;     }
	v_cmp_gt_u32_e64 s[8:9], v52, 8
	v_cmp_gt_f32_e64 s[4:5], v120, v48
	v_cmp_eq_f32_e64 s[6:7], v120, v48
	v_cmp_gt_f32_e64 vcc, v120, v60
	v_cmp_eq_f32_e64 s[12:13], v120, v60
	s_and_b64 s[6:7], s[6:7], s[8:9]
	s_and_b64 s[12:13], s[12:13], s[10:11]
	s_or_b64 s[4:5], s[4:5], s[6:7]
	s_or_b64 vcc, vcc, s[12:13]
	v_addc_co_u32_e64 v128, s[4:5], 0, v128, s[4:5]
	v_addc_co_u32_e32 v129, vcc, 0, v129, vcc
	v_cmp_gt_f32_e64 s[4:5], v120, v50
	v_cmp_eq_f32_e64 s[6:7], v120, v50
	v_cmp_gt_f32_e64 vcc, v120, v54
	v_cmp_eq_f32_e64 s[12:13], v120, v54
	s_and_b64 s[6:7], s[6:7], s[10:11]
	s_and_b64 s[12:13], s[12:13], s[10:11]
	s_or_b64 s[4:5], s[4:5], s[6:7]
	s_or_b64 vcc, vcc, s[12:13]
	v_addc_co_u32_e64 v130, s[4:5], 0, v130, s[4:5]
	v_addc_co_u32_e32 v131, vcc, 0, v131, vcc
	v_cmp_gt_f32_e64 s[4:5], v121, v48
	v_cmp_eq_f32_e64 s[6:7], v121, v48
	v_cmp_gt_f32_e64 vcc, v121, v60
	v_cmp_eq_f32_e64 s[12:13], v121, v60
	s_and_b64 s[6:7], s[6:7], s[8:9]
	s_and_b64 s[12:13], s[12:13], s[8:9]
	s_or_b64 s[4:5], s[4:5], s[6:7]
	s_or_b64 vcc, vcc, s[12:13]
	v_addc_co_u32_e64 v128, s[4:5], 0, v128, s[4:5]
	v_addc_co_u32_e32 v129, vcc, 0, v129, vcc
	v_cmp_gt_f32_e64 s[4:5], v121, v50
	v_cmp_eq_f32_e64 s[6:7], v121, v50
	v_cmp_gt_f32_e64 vcc, v121, v54
	v_cmp_eq_f32_e64 s[12:13], v121, v54
	s_and_b64 s[6:7], s[6:7], s[10:11]
	s_and_b64 s[12:13], s[12:13], s[10:11]
	s_or_b64 s[4:5], s[4:5], s[6:7]
	s_or_b64 vcc, vcc, s[12:13]
	v_addc_co_u32_e64 v130, s[4:5], 0, v130, s[4:5]
	v_addc_co_u32_e32 v131, vcc, 0, v131, vcc
	v_cmp_gt_f32_e64 s[4:5], v122, v48
	v_cmp_eq_f32_e64 s[6:7], v122, v48
	v_cmp_gt_f32_e64 vcc, v122, v60
	v_cmp_eq_f32_e64 s[12:13], v122, v60
	s_and_b64 s[6:7], s[6:7], s[8:9]
	s_and_b64 s[12:13], s[12:13], s[8:9]
	s_or_b64 s[4:5], s[4:5], s[6:7]
	s_or_b64 vcc, vcc, s[12:13]
	v_addc_co_u32_e64 v128, s[4:5], 0, v128, s[4:5]
	v_addc_co_u32_e32 v129, vcc, 0, v129, vcc
	v_cmp_gt_f32_e64 s[4:5], v122, v50
	v_cmp_eq_f32_e64 s[6:7], v122, v50
	v_cmp_gt_f32_e64 vcc, v122, v54
	v_cmp_eq_f32_e64 s[12:13], v122, v54
	s_and_b64 s[6:7], s[6:7], s[8:9]
	s_and_b64 s[12:13], s[12:13], s[10:11]
	s_or_b64 s[4:5], s[4:5], s[6:7]
	s_or_b64 vcc, vcc, s[12:13]
	v_addc_co_u32_e64 v130, s[4:5], 0, v130, s[4:5]
	v_addc_co_u32_e32 v131, vcc, 0, v131, vcc
	v_cmp_gt_f32_e64 s[4:5], v123, v48
	v_cmp_eq_f32_e64 s[6:7], v123, v48
	v_cmp_gt_f32_e64 vcc, v123, v60
	v_cmp_eq_f32_e64 s[12:13], v123, v60
	s_and_b64 s[6:7], s[6:7], s[8:9]
	s_and_b64 s[12:13], s[12:13], s[8:9]
	s_or_b64 s[4:5], s[4:5], s[6:7]
	s_or_b64 vcc, vcc, s[12:13]
	v_addc_co_u32_e64 v128, s[4:5], 0, v128, s[4:5]
	v_addc_co_u32_e32 v129, vcc, 0, v129, vcc
	v_cmp_gt_f32_e64 s[4:5], v123, v50
	v_cmp_eq_f32_e64 s[6:7], v123, v50
	v_cmp_gt_f32_e64 vcc, v123, v54
	v_cmp_eq_f32_e64 s[12:13], v123, v54
	s_and_b64 s[6:7], s[6:7], s[8:9]
	s_and_b64 s[12:13], s[12:13], s[8:9]
	s_or_b64 s[4:5], s[4:5], s[6:7]
	s_or_b64 vcc, vcc, s[12:13]
	v_addc_co_u32_e64 v130, s[4:5], 0, v130, s[4:5]
	v_addc_co_u32_e32 v131, vcc, 0, v131, vcc
	s_waitcnt lgkmcnt(8)
	v_cmp_gt_u32_e64 s[10:11], v52, 12
	v_cmp_gt_f32_e64 s[4:5], v124, v48
	v_cmp_eq_f32_e64 s[6:7], v124, v48
	v_cmp_gt_f32_e64 vcc, v124, v60
	v_cmp_eq_f32_e64 s[12:13], v124, v60
	s_and_b64 s[6:7], s[6:7], s[10:11]
	s_and_b64 s[12:13], s[12:13], s[8:9]
	s_or_b64 s[4:5], s[4:5], s[6:7]
	s_or_b64 vcc, vcc, s[12:13]
	v_addc_co_u32_e64 v128, s[4:5], 0, v128, s[4:5]
	v_addc_co_u32_e32 v129, vcc, 0, v129, vcc
	v_cmp_gt_f32_e64 s[4:5], v124, v50
	v_cmp_eq_f32_e64 s[6:7], v124, v50
	v_cmp_gt_f32_e64 vcc, v124, v54
	v_cmp_eq_f32_e64 s[12:13], v124, v54
	s_and_b64 s[6:7], s[6:7], s[8:9]
	s_and_b64 s[12:13], s[12:13], s[8:9]
	s_or_b64 s[4:5], s[4:5], s[6:7]
	s_or_b64 vcc, vcc, s[12:13]
	v_addc_co_u32_e64 v130, s[4:5], 0, v130, s[4:5]
	v_addc_co_u32_e32 v131, vcc, 0, v131, vcc
	v_cmp_gt_f32_e64 s[4:5], v125, v48
	v_cmp_eq_f32_e64 s[6:7], v125, v48
	v_cmp_gt_f32_e64 vcc, v125, v60
	v_cmp_eq_f32_e64 s[12:13], v125, v60
	s_and_b64 s[6:7], s[6:7], s[10:11]
	s_and_b64 s[12:13], s[12:13], s[10:11]
	s_or_b64 s[4:5], s[4:5], s[6:7]
	s_or_b64 vcc, vcc, s[12:13]
	v_addc_co_u32_e64 v128, s[4:5], 0, v128, s[4:5]
	v_addc_co_u32_e32 v129, vcc, 0, v129, vcc
	v_cmp_gt_f32_e64 s[4:5], v125, v50
	v_cmp_eq_f32_e64 s[6:7], v125, v50
	v_cmp_gt_f32_e64 vcc, v125, v54
	v_cmp_eq_f32_e64 s[12:13], v125, v54
	s_and_b64 s[6:7], s[6:7], s[8:9]
	s_and_b64 s[12:13], s[12:13], s[8:9]
	s_or_b64 s[4:5], s[4:5], s[6:7]
	s_or_b64 vcc, vcc, s[12:13]
	v_addc_co_u32_e64 v130, s[4:5], 0, v130, s[4:5]
	v_addc_co_u32_e32 v131, vcc, 0, v131, vcc
	v_cmp_gt_f32_e64 s[4:5], v126, v48
	v_cmp_eq_f32_e64 s[6:7], v126, v48
	v_cmp_gt_f32_e64 vcc, v126, v60
	v_cmp_eq_f32_e64 s[12:13], v126, v60
	s_and_b64 s[6:7], s[6:7], s[10:11]
	s_and_b64 s[12:13], s[12:13], s[10:11]
	s_or_b64 s[4:5], s[4:5], s[6:7]
	s_or_b64 vcc, vcc, s[12:13]
	v_addc_co_u32_e64 v128, s[4:5], 0, v128, s[4:5]
	v_addc_co_u32_e32 v129, vcc, 0, v129, vcc
	v_cmp_gt_f32_e64 s[4:5], v126, v50
	v_cmp_eq_f32_e64 s[6:7], v126, v50
	v_cmp_gt_f32_e64 vcc, v126, v54
	v_cmp_eq_f32_e64 s[12:13], v126, v54
	s_and_b64 s[6:7], s[6:7], s[10:11]
	s_and_b64 s[12:13], s[12:13], s[8:9]
	s_or_b64 s[4:5], s[4:5], s[6:7]
	s_or_b64 vcc, vcc, s[12:13]
	v_addc_co_u32_e64 v130, s[4:5], 0, v130, s[4:5]
	v_addc_co_u32_e32 v131, vcc, 0, v131, vcc
	v_cmp_gt_f32_e64 s[4:5], v127, v48
	v_cmp_eq_f32_e64 s[6:7], v127, v48
	v_cmp_gt_f32_e64 vcc, v127, v60
	v_cmp_eq_f32_e64 s[12:13], v127, v60
	s_and_b64 s[6:7], s[6:7], s[10:11]
	s_and_b64 s[12:13], s[12:13], s[10:11]
	s_or_b64 s[4:5], s[4:5], s[6:7]
	s_or_b64 vcc, vcc, s[12:13]
	v_addc_co_u32_e64 v128, s[4:5], 0, v128, s[4:5]
	v_addc_co_u32_e32 v129, vcc, 0, v129, vcc
	v_cmp_gt_f32_e64 s[4:5], v127, v50
	v_cmp_eq_f32_e64 s[6:7], v127, v50
	v_cmp_gt_f32_e64 vcc, v127, v54
	v_cmp_eq_f32_e64 s[12:13], v127, v54
	s_and_b64 s[6:7], s[6:7], s[10:11]
	s_and_b64 s[12:13], s[12:13], s[10:11]
	s_or_b64 s[4:5], s[4:5], s[6:7]
	s_or_b64 vcc, vcc, s[12:13]
	v_addc_co_u32_e64 v130, s[4:5], 0, v130, s[4:5]
	v_addc_co_u32_e32 v131, vcc, 0, v131, vcc
	s_waitcnt lgkmcnt(6)
; __device__ __forceinline__ void attn_block(const Params& p, int bt_raw, char* smem) {
;     ...
;     unsigned bits = 0;
; #pragma unroll
;     for (int i = 0; i < 4; ++i) {
;       int J = (lane & 7) * 4 + i;
;       int rank = 0;
; #pragma unroll 1
;       for (int J2 = 0; J2 < 32; ++J2) {
;         float o = imp[tk * 32 + J2];
;         rank += (o > vals[i] || (o == vals[i] && J2 < J)) ? 1 : 0;
;       }
;       if (rank < 8) bits |= (1u << J);
;     }
	v_cmp_gt_u32_e64 s[8:9], v52, 16
	v_cmp_gt_f32_e64 s[4:5], v220, v48
	v_cmp_eq_f32_e64 s[6:7], v220, v48
	v_cmp_gt_f32_e64 vcc, v220, v60
	v_cmp_eq_f32_e64 s[12:13], v220, v60
	s_and_b64 s[6:7], s[6:7], s[8:9]
	s_and_b64 s[12:13], s[12:13], s[10:11]
	s_or_b64 s[4:5], s[4:5], s[6:7]
	s_or_b64 vcc, vcc, s[12:13]
	v_addc_co_u32_e64 v128, s[4:5], 0, v128, s[4:5]
	v_addc_co_u32_e32 v129, vcc, 0, v129, vcc
	v_cmp_gt_f32_e64 s[4:5], v220, v50
	v_cmp_eq_f32_e64 s[6:7], v220, v50
	v_cmp_gt_f32_e64 vcc, v220, v54
	v_cmp_eq_f32_e64 s[12:13], v220, v54
	s_and_b64 s[6:7], s[6:7], s[10:11]
	s_and_b64 s[12:13], s[12:13], s[10:11]
	s_or_b64 s[4:5], s[4:5], s[6:7]
	s_or_b64 vcc, vcc, s[12:13]
	v_addc_co_u32_e64 v130, s[4:5], 0, v130, s[4:5]
	v_addc_co_u32_e32 v131, vcc, 0, v131, vcc
	v_cmp_gt_f32_e64 s[4:5], v221, v48
	v_cmp_eq_f32_e64 s[6:7], v221, v48
	v_cmp_gt_f32_e64 vcc, v221, v60
	v_cmp_eq_f32_e64 s[12:13], v221, v60
	s_and_b64 s[6:7], s[6:7], s[8:9]
	s_and_b64 s[12:13], s[12:13], s[8:9]
	s_or_b64 s[4:5], s[4:5], s[6:7]
	s_or_b64 vcc, vcc, s[12:13]
	v_addc_co_u32_e64 v128, s[4:5], 0, v128, s[4:5]
	v_addc_co_u32_e32 v129, vcc, 0, v129, vcc
	v_cmp_gt_f32_e64 s[4:5], v221, v50
	v_cmp_eq_f32_e64 s[6:7], v221, v50
	v_cmp_gt_f32_e64 vcc, v221, v54
	v_cmp_eq_f32_e64 s[12:13], v221, v54
	s_and_b64 s[6:7], s[6:7], s[10:11]
	s_and_b64 s[12:13], s[12:13], s[10:11]
	s_or_b64 s[4:5], s[4:5], s[6:7]
	s_or_b64 vcc, vcc, s[12:13]
	v_addc_co_u32_e64 v130, s[4:5], 0, v130, s[4:5]
	v_addc_co_u32_e32 v131, vcc, 0, v131, vcc
	v_cmp_gt_f32_e64 s[4:5], v222, v48
	v_cmp_eq_f32_e64 s[6:7], v222, v48
	v_cmp_gt_f32_e64 vcc, v222, v60
	v_cmp_eq_f32_e64 s[12:13], v222, v60
	s_and_b64 s[6:7], s[6:7], s[8:9]
	s_and_b64 s[12:13], s[12:13], s[8:9]
	s_or_b64 s[4:5], s[4:5], s[6:7]
	s_or_b64 vcc, vcc, s[12:13]
	v_addc_co_u32_e64 v128, s[4:5], 0, v128, s[4:5]
	v_addc_co_u32_e32 v129, vcc, 0, v129, vcc
	v_cmp_gt_f32_e64 s[4:5], v222, v50
	v_cmp_eq_f32_e64 s[6:7], v222, v50
	v_cmp_gt_f32_e64 vcc, v222, v54
	v_cmp_eq_f32_e64 s[12:13], v222, v54
	s_and_b64 s[6:7], s[6:7], s[8:9]
	s_and_b64 s[12:13], s[12:13], s[10:11]
	s_or_b64 s[4:5], s[4:5], s[6:7]
	s_or_b64 vcc, vcc, s[12:13]
	v_addc_co_u32_e64 v130, s[4:5], 0, v130, s[4:5]
	v_addc_co_u32_e32 v131, vcc, 0, v131, vcc
	v_cmp_gt_f32_e64 s[4:5], v223, v48
	v_cmp_eq_f32_e64 s[6:7], v223, v48
	v_cmp_gt_f32_e64 vcc, v223, v60
	v_cmp_eq_f32_e64 s[12:13], v223, v60
	s_and_b64 s[6:7], s[6:7], s[8:9]
	s_and_b64 s[12:13], s[12:13], s[8:9]
	s_or_b64 s[4:5], s[4:5], s[6:7]
	s_or_b64 vcc, vcc, s[12:13]
	v_addc_co_u32_e64 v128, s[4:5], 0, v128, s[4:5]
	v_addc_co_u32_e32 v129, vcc, 0, v129, vcc
	v_cmp_gt_f32_e64 s[4:5], v223, v50
	v_cmp_eq_f32_e64 s[6:7], v223, v50
	v_cmp_gt_f32_e64 vcc, v223, v54
	v_cmp_eq_f32_e64 s[12:13], v223, v54
	s_and_b64 s[6:7], s[6:7], s[8:9]
	s_and_b64 s[12:13], s[12:13], s[8:9]
	s_or_b64 s[4:5], s[4:5], s[6:7]
	s_or_b64 vcc, vcc, s[12:13]
	v_addc_co_u32_e64 v130, s[4:5], 0, v130, s[4:5]
	v_addc_co_u32_e32 v131, vcc, 0, v131, vcc
	s_waitcnt lgkmcnt(4)
	v_cmp_gt_u32_e64 s[10:11], v52, 20
	v_cmp_gt_f32_e64 s[4:5], v224, v48
	v_cmp_eq_f32_e64 s[6:7], v224, v48
	v_cmp_gt_f32_e64 vcc, v224, v60
	v_cmp_eq_f32_e64 s[12:13], v224, v60
	s_and_b64 s[6:7], s[6:7], s[10:11]
	s_and_b64 s[12:13], s[12:13], s[8:9]
	s_or_b64 s[4:5], s[4:5], s[6:7]
	s_or_b64 vcc, vcc, s[12:13]
	v_addc_co_u32_e64 v128, s[4:5], 0, v128, s[4:5]
	v_addc_co_u32_e32 v129, vcc, 0, v129, vcc
	v_cmp_gt_f32_e64 s[4:5], v224, v50
	v_cmp_eq_f32_e64 s[6:7], v224, v50
	v_cmp_gt_f32_e64 vcc, v224, v54
	v_cmp_eq_f32_e64 s[12:13], v224, v54
	s_and_b64 s[6:7], s[6:7], s[8:9]
	s_and_b64 s[12:13], s[12:13], s[8:9]
	s_or_b64 s[4:5], s[4:5], s[6:7]
	s_or_b64 vcc, vcc, s[12:13]
	v_addc_co_u32_e64 v130, s[4:5], 0, v130, s[4:5]
	v_addc_co_u32_e32 v131, vcc, 0, v131, vcc
	v_cmp_gt_f32_e64 s[4:5], v225, v48
	v_cmp_eq_f32_e64 s[6:7], v225, v48
	v_cmp_gt_f32_e64 vcc, v225, v60
	v_cmp_eq_f32_e64 s[12:13], v225, v60
	s_and_b64 s[6:7], s[6:7], s[10:11]
	s_and_b64 s[12:13], s[12:13], s[10:11]
	s_or_b64 s[4:5], s[4:5], s[6:7]
	s_or_b64 vcc, vcc, s[12:13]
	v_addc_co_u32_e64 v128, s[4:5], 0, v128, s[4:5]
	v_addc_co_u32_e32 v129, vcc, 0, v129, vcc
	v_cmp_gt_f32_e64 s[4:5], v225, v50
	v_cmp_eq_f32_e64 s[6:7], v225, v50
	v_cmp_gt_f32_e64 vcc, v225, v54
	v_cmp_eq_f32_e64 s[12:13], v225, v54
	s_and_b64 s[6:7], s[6:7], s[8:9]
	s_and_b64 s[12:13], s[12:13], s[8:9]
	s_or_b64 s[4:5], s[4:5], s[6:7]
	s_or_b64 vcc, vcc, s[12:13]
	v_addc_co_u32_e64 v130, s[4:5], 0, v130, s[4:5]
	v_addc_co_u32_e32 v131, vcc, 0, v131, vcc
	v_cmp_gt_f32_e64 s[4:5], v226, v48
	v_cmp_eq_f32_e64 s[6:7], v226, v48
	v_cmp_gt_f32_e64 vcc, v226, v60
	v_cmp_eq_f32_e64 s[12:13], v226, v60
	s_and_b64 s[6:7], s[6:7], s[10:11]
	s_and_b64 s[12:13], s[12:13], s[10:11]
	s_or_b64 s[4:5], s[4:5], s[6:7]
	s_or_b64 vcc, vcc, s[12:13]
	v_addc_co_u32_e64 v128, s[4:5], 0, v128, s[4:5]
	v_addc_co_u32_e32 v129, vcc, 0, v129, vcc
	v_cmp_gt_f32_e64 s[4:5], v226, v50
	v_cmp_eq_f32_e64 s[6:7], v226, v50
	v_cmp_gt_f32_e64 vcc, v226, v54
	v_cmp_eq_f32_e64 s[12:13], v226, v54
	s_and_b64 s[6:7], s[6:7], s[10:11]
	s_and_b64 s[12:13], s[12:13], s[8:9]
	s_or_b64 s[4:5], s[4:5], s[6:7]
	s_or_b64 vcc, vcc, s[12:13]
	v_addc_co_u32_e64 v130, s[4:5], 0, v130, s[4:5]
	v_addc_co_u32_e32 v131, vcc, 0, v131, vcc
	v_cmp_gt_f32_e64 s[4:5], v227, v48
	v_cmp_eq_f32_e64 s[6:7], v227, v48
	v_cmp_gt_f32_e64 vcc, v227, v60
	v_cmp_eq_f32_e64 s[12:13], v227, v60
	s_and_b64 s[6:7], s[6:7], s[10:11]
	s_and_b64 s[12:13], s[12:13], s[10:11]
	s_or_b64 s[4:5], s[4:5], s[6:7]
	s_or_b64 vcc, vcc, s[12:13]
	v_addc_co_u32_e64 v128, s[4:5], 0, v128, s[4:5]
	v_addc_co_u32_e32 v129, vcc, 0, v129, vcc
	v_cmp_gt_f32_e64 s[4:5], v227, v50
	v_cmp_eq_f32_e64 s[6:7], v227, v50
	v_cmp_gt_f32_e64 vcc, v227, v54
	v_cmp_eq_f32_e64 s[12:13], v227, v54
	s_and_b64 s[6:7], s[6:7], s[10:11]
	s_and_b64 s[12:13], s[12:13], s[10:11]
	s_or_b64 s[4:5], s[4:5], s[6:7]
	s_or_b64 vcc, vcc, s[12:13]
	v_addc_co_u32_e64 v130, s[4:5], 0, v130, s[4:5]
	v_addc_co_u32_e32 v131, vcc, 0, v131, vcc
	s_waitcnt lgkmcnt(2)
; __device__ __forceinline__ void attn_block(const Params& p, int bt_raw, char* smem) {
;     ...
;     unsigned bits = 0;
; #pragma unroll
;     for (int i = 0; i < 4; ++i) {
;       int J = (lane & 7) * 4 + i;
;       int rank = 0;
; #pragma unroll 1
;       for (int J2 = 0; J2 < 32; ++J2) {
;         float o = imp[tk * 32 + J2];
;         rank += (o > vals[i] || (o == vals[i] && J2 < J)) ? 1 : 0;
;       }
;       if (rank < 8) bits |= (1u << J);
;     }
;     bits |= __shfl_xor(bits, 1);
;     bits |= __shfl_xor(bits, 2);
;     bits |= __shfl_xor(bits, 4);
;     if ((lane & 7) == 0) msk[tk] = bits;
	v_cmp_gt_u32_e64 s[8:9], v52, 24
	v_cmp_gt_f32_e64 s[4:5], v228, v48
	v_cmp_eq_f32_e64 s[6:7], v228, v48
	v_cmp_gt_f32_e64 vcc, v228, v60
	v_cmp_eq_f32_e64 s[12:13], v228, v60
	s_and_b64 s[6:7], s[6:7], s[8:9]
	s_and_b64 s[12:13], s[12:13], s[10:11]
	s_or_b64 s[4:5], s[4:5], s[6:7]
	s_or_b64 vcc, vcc, s[12:13]
	v_addc_co_u32_e64 v128, s[4:5], 0, v128, s[4:5]
	v_addc_co_u32_e32 v129, vcc, 0, v129, vcc
	v_cmp_gt_f32_e64 s[4:5], v228, v50
	v_cmp_eq_f32_e64 s[6:7], v228, v50
	v_cmp_gt_f32_e64 vcc, v228, v54
	v_cmp_eq_f32_e64 s[12:13], v228, v54
	s_and_b64 s[6:7], s[6:7], s[10:11]
	s_and_b64 s[12:13], s[12:13], s[10:11]
	s_or_b64 s[4:5], s[4:5], s[6:7]
	s_or_b64 vcc, vcc, s[12:13]
	v_addc_co_u32_e64 v130, s[4:5], 0, v130, s[4:5]
	v_addc_co_u32_e32 v131, vcc, 0, v131, vcc
	v_cmp_gt_f32_e64 s[4:5], v229, v48
	v_cmp_eq_f32_e64 s[6:7], v229, v48
	v_cmp_gt_f32_e64 vcc, v229, v60
	v_cmp_eq_f32_e64 s[12:13], v229, v60
	s_and_b64 s[6:7], s[6:7], s[8:9]
	s_and_b64 s[12:13], s[12:13], s[8:9]
	s_or_b64 s[4:5], s[4:5], s[6:7]
	s_or_b64 vcc, vcc, s[12:13]
	v_addc_co_u32_e64 v128, s[4:5], 0, v128, s[4:5]
	v_addc_co_u32_e32 v129, vcc, 0, v129, vcc
	v_cmp_gt_f32_e64 s[4:5], v229, v50
	v_cmp_eq_f32_e64 s[6:7], v229, v50
	v_cmp_gt_f32_e64 vcc, v229, v54
	v_cmp_eq_f32_e64 s[12:13], v229, v54
	s_and_b64 s[6:7], s[6:7], s[10:11]
	s_and_b64 s[12:13], s[12:13], s[10:11]
	s_or_b64 s[4:5], s[4:5], s[6:7]
	s_or_b64 vcc, vcc, s[12:13]
	v_addc_co_u32_e64 v130, s[4:5], 0, v130, s[4:5]
	v_addc_co_u32_e32 v131, vcc, 0, v131, vcc
	v_cmp_gt_f32_e64 s[4:5], v230, v48
	v_cmp_eq_f32_e64 s[6:7], v230, v48
	v_cmp_gt_f32_e64 vcc, v230, v60
	v_cmp_eq_f32_e64 s[12:13], v230, v60
	s_and_b64 s[6:7], s[6:7], s[8:9]
	s_and_b64 s[12:13], s[12:13], s[8:9]
	s_or_b64 s[4:5], s[4:5], s[6:7]
	s_or_b64 vcc, vcc, s[12:13]
	v_addc_co_u32_e64 v128, s[4:5], 0, v128, s[4:5]
	v_addc_co_u32_e32 v129, vcc, 0, v129, vcc
	v_cmp_gt_f32_e64 s[4:5], v230, v50
	v_cmp_eq_f32_e64 s[6:7], v230, v50
	v_cmp_gt_f32_e64 vcc, v230, v54
	v_cmp_eq_f32_e64 s[12:13], v230, v54
	s_and_b64 s[6:7], s[6:7], s[8:9]
	s_and_b64 s[12:13], s[12:13], s[10:11]
	s_or_b64 s[4:5], s[4:5], s[6:7]
	s_or_b64 vcc, vcc, s[12:13]
	v_addc_co_u32_e64 v130, s[4:5], 0, v130, s[4:5]
	v_addc_co_u32_e32 v131, vcc, 0, v131, vcc
	v_cmp_gt_f32_e64 s[4:5], v231, v48
	v_cmp_eq_f32_e64 s[6:7], v231, v48
	v_cmp_gt_f32_e64 vcc, v231, v60
	v_cmp_eq_f32_e64 s[12:13], v231, v60
	s_and_b64 s[6:7], s[6:7], s[8:9]
	s_and_b64 s[12:13], s[12:13], s[8:9]
	s_or_b64 s[4:5], s[4:5], s[6:7]
	s_or_b64 vcc, vcc, s[12:13]
	v_addc_co_u32_e64 v128, s[4:5], 0, v128, s[4:5]
	v_addc_co_u32_e32 v129, vcc, 0, v129, vcc
	v_cmp_gt_f32_e64 s[4:5], v231, v50
	v_cmp_eq_f32_e64 s[6:7], v231, v50
	v_cmp_gt_f32_e64 vcc, v231, v54
	v_cmp_eq_f32_e64 s[12:13], v231, v54
	s_and_b64 s[6:7], s[6:7], s[8:9]
	s_and_b64 s[12:13], s[12:13], s[8:9]
	s_or_b64 s[4:5], s[4:5], s[6:7]
	s_or_b64 vcc, vcc, s[12:13]
	v_addc_co_u32_e64 v130, s[4:5], 0, v130, s[4:5]
	v_addc_co_u32_e32 v131, vcc, 0, v131, vcc
	s_waitcnt lgkmcnt(0)
	v_cmp_gt_f32_e64 s[4:5], v232, v48
	v_cmp_gt_f32_e64 vcc, v232, v60
	v_cmp_eq_f32_e64 s[12:13], v232, v60
	s_and_b64 s[12:13], s[12:13], s[8:9]
	s_or_b64 vcc, vcc, s[12:13]
	v_addc_co_u32_e64 v128, s[4:5], 0, v128, s[4:5]
	v_addc_co_u32_e32 v129, vcc, 0, v129, vcc
	v_cmp_gt_f32_e64 s[4:5], v232, v50
	v_cmp_eq_f32_e64 s[6:7], v232, v50
	v_cmp_gt_f32_e64 vcc, v232, v54
	v_cmp_eq_f32_e64 s[12:13], v232, v54
	s_and_b64 s[6:7], s[6:7], s[8:9]
	s_and_b64 s[12:13], s[12:13], s[8:9]
	s_or_b64 s[4:5], s[4:5], s[6:7]
	s_or_b64 vcc, vcc, s[12:13]
	v_addc_co_u32_e64 v130, s[4:5], 0, v130, s[4:5]
	v_addc_co_u32_e32 v131, vcc, 0, v131, vcc
	v_cmp_gt_f32_e64 s[4:5], v233, v48
	v_cmp_gt_f32_e64 vcc, v233, v60
	s_nop 1
	v_addc_co_u32_e64 v128, s[4:5], 0, v128, s[4:5]
	v_addc_co_u32_e32 v129, vcc, 0, v129, vcc
	v_cmp_gt_f32_e64 s[4:5], v233, v50
	v_cmp_eq_f32_e64 s[6:7], v233, v50
	v_cmp_gt_f32_e64 vcc, v233, v54
	v_cmp_eq_f32_e64 s[12:13], v233, v54
	s_and_b64 s[6:7], s[6:7], s[8:9]
	s_and_b64 s[12:13], s[12:13], s[8:9]
	s_or_b64 s[4:5], s[4:5], s[6:7]
	s_or_b64 vcc, vcc, s[12:13]
	v_addc_co_u32_e64 v130, s[4:5], 0, v130, s[4:5]
	v_addc_co_u32_e32 v131, vcc, 0, v131, vcc
	v_cmp_gt_f32_e64 s[4:5], v234, v48
	v_cmp_gt_f32_e64 vcc, v234, v60
	s_nop 1
	v_addc_co_u32_e64 v128, s[4:5], 0, v128, s[4:5]
	v_addc_co_u32_e32 v129, vcc, 0, v129, vcc
	v_cmp_gt_f32_e64 s[4:5], v234, v50
	v_cmp_gt_f32_e64 vcc, v234, v54
	v_cmp_eq_f32_e64 s[12:13], v234, v54
	s_and_b64 s[12:13], s[12:13], s[8:9]
	s_or_b64 vcc, vcc, s[12:13]
	v_addc_co_u32_e64 v130, s[4:5], 0, v130, s[4:5]
	v_addc_co_u32_e32 v131, vcc, 0, v131, vcc
	v_cmp_gt_f32_e64 s[4:5], v235, v48
	v_cmp_gt_f32_e64 vcc, v235, v60
	s_nop 1
	v_addc_co_u32_e64 v128, s[4:5], 0, v128, s[4:5]
	v_addc_co_u32_e32 v129, vcc, 0, v129, vcc
	v_cmp_gt_f32_e64 s[4:5], v235, v50
	v_cmp_gt_f32_e64 vcc, v235, v54
	s_nop 1
	v_addc_co_u32_e64 v130, s[4:5], 0, v130, s[4:5]
	v_addc_co_u32_e32 v131, vcc, 0, v131, vcc
	v_mov_b32_e32 v59, v128
	v_mov_b32_e32 v48, v129
	v_mov_b32_e32 v62, 0
	v_mov_b32_e32 v60, v130
	v_mov_b32_e32 v63, 0
	v_mov_b32_e32 v50, v131
	v_mov_b32_e32 v58, 0
	s_movk_i32 s20, 0x80
	s_mov_b32 s28, 32
	s_mov_b32 s15, 33
	v_add_u32_e32 v49, v59, v61
	v_lshlrev_b32_e64 v51, v52, 1
	v_add_u32_e32 v48, v48, v62
	v_cmp_gt_u32_e32 vcc, 8, v49
	v_add_u32_e32 v54, v60, v63
	v_add_u32_e32 v50, v50, v58
	v_cndmask_b32_e32 v49, 0, v51, vcc
	v_lshlrev_b32_e64 v51, v52, 2
	v_cmp_gt_u32_e32 vcc, 8, v48
	s_nop 1
	v_cndmask_b32_e32 v48, 0, v51, vcc
	v_or_b32_e32 v48, v48, v49
	v_lshlrev_b32_e64 v49, v52, 4
	v_cmp_gt_u32_e32 vcc, 8, v54
	v_lshlrev_b32_e64 v51, v52, 8
	s_nop 0
	v_cndmask_b32_e32 v49, 0, v49, vcc
	v_cmp_gt_u32_e32 vcc, 8, v50
	s_nop 1
	v_cndmask_b32_e32 v50, 0, v51, vcc
	v_or3_b32 v48, v48, v49, v50
	v_xor_b32_e32 v49, 1, v198
	v_cmp_lt_i32_e32 vcc, v49, v186
	v_and_b32_e32 v50, 7, v181
	s_nop 0
	v_cndmask_b32_e32 v49, v198, v49, vcc
	v_lshlrev_b32_e32 v49, 2, v49
	ds_bpermute_b32 v49, v49, v48
	s_waitcnt lgkmcnt(0)
	v_or_b32_e32 v48, v49, v48
	v_xor_b32_e32 v49, 2, v198
	v_cmp_lt_i32_e32 vcc, v49, v186
	s_nop 1
	v_cndmask_b32_e32 v49, v198, v49, vcc
	v_lshlrev_b32_e32 v49, 2, v49
	ds_bpermute_b32 v49, v49, v48
	v_cmp_eq_u32_e32 vcc, 0, v50
	s_waitcnt lgkmcnt(0)
	v_or_b32_e32 v48, v48, v49
	ds_bpermute_b32 v49, v188, v48
	s_and_saveexec_b64 s[4:5], vcc
	s_cbranch_execz .LBB0_344
	s_movk_i32 s6, 0xff84
	s_waitcnt lgkmcnt(0)
	v_or_b32_e32 v48, v48, v49
	v_mad_i32_i24 v49, v53, s6, v55
	ds_write_b32 v49, v48 offset:1024
